# attention unit prologues: q_norm_g rows, late Q pieces and output-gate loads issued with the first load batch (on top of the pipelined GEMM2 hook)
# speedup vs baseline: 1.0091x; 1.0091x over previous
.LBB0_446:
	s_and_b64 vcc, exec, s[0:1]
	s_cbranch_vccz .LBB0_458
	s_add_i32 s0, s9, 0xfffffd40
	s_lshr_b32 s0, s0, 4
	s_and_b32 s1, s9, 1
	v_ashrrev_i32_e32 v3, 6, v130
	v_and_b32_e32 v4, 15, v130
	s_lshl_b32 s2, s0, 8
	s_lshl_b32 s3, s1, 7
	s_waitcnt vmcnt(0)
	v_lshlrev_b32_e32 v18, 4, v3
	v_or_b32_e32 v1, v18, v4
	s_or_b32 s3, s2, s3
	v_add_u32_e32 v128, s3, v1
	v_lshlrev_b32_e32 v1, 4, v130
	s_lshl_b32 s3, s9, 6
	v_cmp_lt_i32_e32 vcc, v234, v229
	v_and_b32_e32 v5, 0x70, v1
	s_and_b32 s4, s3, 0x380
	s_or_b32 s3, s2, 64
	v_cndmask_b32_e32 v1, v228, v234, vcc
	v_cmp_lt_i32_e32 vcc, v235, v229
	s_cmp_eq_u32 s1, 0
	s_cselect_b64 s[28:29], -1, 0
	v_cndmask_b32_e32 v7, v228, v235, vcc
	v_cmp_lt_i32_e32 vcc, v230, v229
	v_lshlrev_b32_e32 v125, 2, v7
	s_lshl_b32 s0, s0, 9
	v_cndmask_b32_e32 v7, v228, v230, vcc
	v_cmp_lt_i32_e32 vcc, v231, v229
	v_readlane_b32 s1, v252, 17
	v_ashrrev_i32_e32 v6, 3, v130
	v_lshlrev_b32_e32 v131, 2, v7
	v_cndmask_b32_e32 v7, v228, v231, vcc
	v_cmp_lt_i32_e32 vcc, v232, v229
	s_add_i32 s0, s0, s1
	v_lshlrev_b32_e32 v147, 2, v7
	v_cndmask_b32_e32 v7, v228, v232, vcc
	v_add_u32_e32 v149, s0, v6
	s_movk_i32 s0, 0x110
	v_lshlrev_b32_e32 v148, 2, v7
	v_mul_lo_u32 v7, v6, s0
	s_movk_i32 s0, 0x900
	v_and_b32_e32 v2, 63, v130
	v_mul_lo_u32 v3, v3, s0
	s_or_b32 s0, s2, 0x80
	v_lshlrev_b32_e32 v62, 1, v5
	v_add_u32_e32 v91, s0, v6
	v_or_b32_e32 v90, s0, v2
	s_or_b32 s0, s2, 0xc0
	v_bfe_u32 v54, v130, 4, 2
	v_add3_u32 v150, 0, v62, v7
	v_lshlrev_b32_e32 v7, 1, v2
	v_add_u32_e32 v89, s0, v6
	v_or_b32_e32 v88, s0, v2
	v_readlane_b32 s0, v252, 22
	v_or_b32_e32 v22, s2, v2
	v_lshlrev_b32_e32 v50, 3, v54
	v_add3_u32 v151, 0, v3, v7
	v_mul_u32_u24_e32 v3, 0x90, v4
	v_lshlrev_b32_e32 v64, 2, v5
	v_readlane_b32 s1, v252, 23
	v_mov_b64_e32 v[78:79], s[94:95]
	v_add_u32_e32 v20, s2, v6
	v_ashrrev_i32_e32 v19, 31, v18
	v_add_u32_e32 v30, s3, v6
	v_or_b32_e32 v31, s3, v2
	v_mul_u32_u24_e32 v87, 0x110, v4
	v_add3_u32 v152, 0, v50, v3
	global_load_dwordx4 v[2:5], v64, s[0:1] offset:48
	global_load_dwordx4 v[6:9], v64, s[0:1] offset:32
	global_load_dwordx4 v[10:13], v64, s[0:1] offset:16
	global_load_dwordx4 v[14:17], v64, s[0:1]
	v_readlane_b32 s100, v252, 20
	v_readlane_b32 s101, v252, 21
	v_lshlrev_b32_e32 v146, 5, v54
	s_nop 4
	global_load_dwordx4 v[158:161], v146, s[100:101] offset:16
	global_load_dwordx4 v[162:165], v146, s[100:101]
	global_load_dwordx4 v[166:169], v146, s[100:101] offset:144
	global_load_dwordx4 v[170:173], v146, s[100:101] offset:128
	global_load_dwordx4 v[174:177], v146, s[100:101] offset:272
	global_load_dwordx4 v[178:181], v146, s[100:101] offset:256
	global_load_dwordx4 v[182:185], v146, s[100:101] offset:400
	global_load_dwordx4 v[186:189], v146, s[100:101] offset:384
	s_lshl_b32 s34, s4, 1
	v_mad_u64_u32 v[22:23], s[0:1], v22, s20, v[78:79]
	v_lshl_add_u64 v[22:23], v[22:23], 0, s[34:35]
	v_lshlrev_b64 v[80:81], 1, v[18:19]
	v_mad_i64_i32 v[20:21], s[0:1], v20, s20, v[78:79]
	v_lshl_add_u64 v[26:27], v[22:23], 0, v[80:81]
	s_movk_i32 s2, 0x1000
	v_lshl_add_u64 v[20:21], v[20:21], 0, s[34:35]
	v_lshl_add_u64 v[28:29], v[26:27], 0, s[26:27]
	v_mov_b32_e32 v63, v0
	v_add_co_u32_e32 v26, vcc, s2, v26
	v_lshl_add_u64 v[22:23], v[20:21], 0, v[62:63]
	s_nop 0
	v_addc_co_u32_e32 v27, vcc, 0, v27, vcc
	global_load_dwordx4 v[18:21], v[22:23], off offset:2064
	s_nop 0
	global_load_dwordx4 v[22:25], v[22:23], off offset:2048
	s_nop 0
	global_load_dwordx4 v[34:37], v[26:27], off
	global_load_dwordx4 v[38:41], v[28:29], off offset:16
	v_mad_u64_u32 v[28:29], s[0:1], v31, s20, v[78:79]
	v_lshl_add_u64 v[28:29], v[28:29], 0, s[34:35]
	v_lshl_add_u64 v[42:43], v[28:29], 0, v[80:81]
	v_mad_i64_i32 v[56:57], s[0:1], v128, s20, v[78:79]
	v_mad_i64_i32 v[26:27], s[0:1], v30, s20, v[78:79]
	v_lshl_add_u64 v[46:47], v[42:43], 0, s[26:27]
	v_add_co_u32_e32 v42, vcc, s2, v42
	v_mov_b32_e32 v51, v0
	v_lshl_add_u64 v[56:57], v[56:57], 0, s[34:35]
	v_addc_co_u32_e32 v43, vcc, 0, v43, vcc
	v_lshl_add_u64 v[50:51], v[56:57], 0, v[50:51]
	s_mov_b64 s[0:1], 0x1800
	v_lshl_add_u64 v[26:27], v[26:27], 0, s[34:35]
	v_lshl_add_u64 v[58:59], v[50:51], 0, s[0:1]
	v_add_co_u32_e32 v50, vcc, s2, v50
	v_and_b32_e32 v52, 48, v130
	v_lshl_add_u64 v[30:31], v[26:27], 0, v[62:63]
	v_addc_co_u32_e32 v51, vcc, 0, v51, vcc
	v_mov_b32_e32 v53, v0
	global_load_dwordx4 v[26:29], v[30:31], off offset:2064
	s_nop 0
	global_load_dwordx4 v[30:33], v[30:31], off offset:2048
	s_nop 0
	global_load_dwordx4 v[42:45], v[42:43], off
	s_nop 0
	global_load_dwordx4 v[46:49], v[46:47], off offset:16
	s_nop 0
	global_load_dwordx2 v[134:135], v[50:51], off offset:2048
	global_load_dwordx2 v[132:133], v[58:59], off offset:32
	global_load_dwordx2 v[126:127], v[58:59], off offset:64
	global_load_dwordx2 v[122:123], v[58:59], off offset:96
	global_load_dwordx2 v[120:121], v[58:59], off offset:128
	global_load_dwordx2 v[118:119], v[58:59], off offset:160
	global_load_dwordx2 v[116:117], v[58:59], off offset:192
	global_load_dwordx2 v[114:115], v[58:59], off offset:224
	v_lshl_add_u64 v[50:51], v[56:57], 0, v[52:53]
	global_load_dwordx4 v[68:71], v[50:51], off
	global_load_dwordx4 v[72:75], v[50:51], off offset:64
	global_load_dwordx4 v[190:193], v[50:51], off offset:128
	global_load_dwordx4 v[106:109], v[50:51], off offset:192
	v_add_u32_e32 v86, 0, v52
	v_lshlrev_b32_e32 v1, 2, v1
	s_mov_b32 s0, 0x800000
	v_lshlrev_b32_e32 v105, 5, v54
	v_lshlrev_b32_e32 v124, 2, v54
	v_mov_b32_e32 v65, v0
	v_mov_b32_e32 v156, 0
	v_ashrrev_i32_e32 v129, 31, v128
	s_mov_b32 s5, 0
	v_add_u32_e32 v153, 0xd400, v152
	v_add_u32_e32 v154, 64, v149
	s_mov_b64 s[2:3], -1
	v_mov_b32_e32 v157, 0xf149f2ca
	v_add_u32_e32 v155, v86, v87
	v_mov_b32_e32 v86, 0
	v_mov_b32_e32 v87, v156
	s_waitcnt vmcnt(0)
	v_lshlrev_b32_e32 v67, 16, v69
	v_and_b32_e32 v66, 0xffff0000, v69
	v_lshlrev_b32_e32 v61, 16, v70
	v_and_b32_e32 v60, 0xffff0000, v70
	v_lshlrev_b32_e32 v59, 16, v71
	v_and_b32_e32 v58, 0xffff0000, v71
	v_lshlrev_b32_e32 v94, 16, v72
	v_and_b32_e32 v93, 0xffff0000, v72
	v_lshlrev_b32_e32 v72, 16, v74
	v_and_b32_e32 v71, 0xffff0000, v74
	v_lshlrev_b32_e32 v70, 16, v75
	v_and_b32_e32 v69, 0xffff0000, v75
	v_mov_b64_e32 v[74:75], v[190:191]
	v_mov_b64_e32 v[76:77], v[192:193]
	v_lshlrev_b32_e32 v55, 16, v68
	v_mov_b64_e32 v[50:51], v[106:107]
	v_mov_b64_e32 v[52:53], v[108:109]
	v_and_b32_e32 v68, 0xffff0000, v68
	v_mul_f32_e32 v82, v68, v68
	v_fmac_f32_e32 v82, v55, v55
	v_fmac_f32_e32 v82, v67, v67
	v_fmac_f32_e32 v82, v66, v66
	v_fmac_f32_e32 v82, v61, v61
	v_fmac_f32_e32 v82, v60, v60
	v_fmac_f32_e32 v82, v59, v59
	v_fmac_f32_e32 v82, v58, v58
	v_fmac_f32_e32 v82, v94, v94
	v_lshlrev_b32_e32 v92, 16, v73
	v_fmac_f32_e32 v82, v93, v93
	v_and_b32_e32 v73, 0xffff0000, v73
	v_fmac_f32_e32 v82, v92, v92
	v_fmac_f32_e32 v82, v73, v73
	v_fmac_f32_e32 v82, v72, v72
	v_fmac_f32_e32 v82, v71, v71
	v_fmac_f32_e32 v82, v70, v70
	v_fmac_f32_e32 v82, v69, v69
	s_waitcnt vmcnt(1)
	v_lshlrev_b32_e32 v102, 16, v74
	v_and_b32_e32 v101, 0xffff0000, v74
	v_fmac_f32_e32 v82, v102, v102
	v_lshlrev_b32_e32 v100, 16, v75
	v_fmac_f32_e32 v82, v101, v101
	v_and_b32_e32 v99, 0xffff0000, v75
	v_fmac_f32_e32 v82, v100, v100
	v_lshlrev_b32_e32 v98, 16, v76
	v_fmac_f32_e32 v82, v99, v99
	v_and_b32_e32 v97, 0xffff0000, v76
	v_fmac_f32_e32 v82, v98, v98
	v_lshlrev_b32_e32 v96, 16, v77
	v_fmac_f32_e32 v82, v97, v97
	v_and_b32_e32 v95, 0xffff0000, v77
	v_fmac_f32_e32 v82, v96, v96
	s_waitcnt vmcnt(0)
	v_and_b32_e32 v74, 0xffff0000, v50
	v_lshlrev_b32_e32 v75, 16, v50
	v_fmac_f32_e32 v82, v95, v95
	v_pk_mul_f32 v[56:57], v[74:75], v[74:75]
	v_and_b32_e32 v76, 0xffff0000, v51
	v_add_f32_e32 v50, v57, v82
	v_lshlrev_b32_e32 v77, 16, v51
	v_add_f32_e32 v56, v56, v50
	v_pk_mul_f32 v[50:51], v[76:77], v[76:77]
	v_and_b32_e32 v82, 0xffff0000, v52
	v_add_f32_e32 v51, v51, v56
	v_lshlrev_b32_e32 v83, 16, v52
	v_add_f32_e32 v56, v50, v51
	v_pk_mul_f32 v[50:51], v[82:83], v[82:83]
	v_and_b32_e32 v84, 0xffff0000, v53
	v_add_f32_e32 v51, v51, v56
	v_lshlrev_b32_e32 v85, 16, v53
	v_add_f32_e32 v52, v50, v51
	v_pk_mul_f32 v[50:51], v[84:85], v[84:85]
	s_nop 0
	v_add_f32_e32 v51, v51, v52
	v_add_f32_e32 v50, v50, v51
	ds_bpermute_b32 v51, v1, v50
	s_waitcnt lgkmcnt(0)
	v_add_f32_e32 v50, v50, v51
	ds_bpermute_b32 v51, v125, v50
	s_waitcnt lgkmcnt(0)
	v_add_f32_e32 v50, v50, v51
	v_fmamk_f32 v50, v50, 0x3c000000, v221
	v_cmp_gt_f32_e32 vcc, s0, v50
	v_mul_f32_e32 v51, 0x4b800000, v50
	v_readlane_b32 s0, v252, 20
	v_cndmask_b32_e32 v50, v50, v51, vcc
	v_rsq_f32_e32 v50, v50
	v_readlane_b32 s1, v252, 21
	v_mul_f32_e32 v51, 0x45800000, v50
	v_cndmask_b32_e32 v50, v50, v51, vcc
	v_mul_f32_e32 v103, 0x3e0293ee, v50
	v_mul_f32_e32 v104, v103, v55
	s_nop 0
	v_mov_b64_e32 v[50:51], v[158:159]
	v_mov_b64_e32 v[52:53], v[160:161]
	v_mov_b64_e32 v[54:55], v[162:163]
	v_mov_b64_e32 v[56:57], v[164:165]
	v_mul_f32_e32 v68, v103, v68
	v_mul_f32_e32 v67, v103, v67
	v_mul_f32_e32 v66, v103, v66
	v_mul_f32_e32 v61, v103, v61
	v_mul_f32_e32 v60, v103, v60
	v_mul_f32_e32 v59, v103, v59
	v_mul_f32_e32 v58, v103, v58
	v_mul_f32_e32 v74, v103, v74
	v_mul_f32_e32 v75, v103, v75
	s_waitcnt vmcnt(1)
	v_mul_f32_e32 v50, v50, v61
	s_waitcnt vmcnt(0)
	v_mul_f32_e32 v54, v54, v104
	v_mul_f32_e32 v55, v55, v68
	v_mul_f32_e32 v56, v56, v67
	v_mul_f32_e32 v57, v57, v66
	v_mul_f32_e32 v51, v51, v60
	v_mul_f32_e32 v52, v52, v59
	v_mul_f32_e32 v53, v53, v58
	v_cvt_pk_bf16_f32 v58, v54, v55
	v_cvt_pk_bf16_f32 v59, v56, v57
	v_cvt_pk_bf16_f32 v60, v50, v51
	v_cvt_pk_bf16_f32 v61, v52, v53
	v_mov_b64_e32 v[50:51], v[166:167]
	v_mov_b64_e32 v[52:53], v[168:169]
	v_mov_b64_e32 v[54:55], v[170:171]
	v_mov_b64_e32 v[56:57], v[172:173]
	v_mul_f32_e32 v66, v103, v94
	v_mov_b32_e32 v94, 0
	s_waitcnt vmcnt(0)
	v_mul_f32_e32 v54, v54, v66
	v_mul_f32_e32 v66, v103, v93
	v_mul_f32_e32 v55, v55, v66
	v_mul_f32_e32 v66, v103, v92
	v_mul_f32_e32 v56, v56, v66
	v_mul_f32_e32 v66, v103, v73
	v_mul_f32_e32 v57, v57, v66
	v_mul_f32_e32 v66, v103, v72
	v_mul_f32_e32 v50, v50, v66
	v_mul_f32_e32 v66, v103, v71
	v_mul_f32_e32 v51, v51, v66
	v_mul_f32_e32 v66, v103, v70
	v_mul_f32_e32 v52, v52, v66
	v_mul_f32_e32 v66, v103, v69
	v_mul_f32_e32 v53, v53, v66
	v_cvt_pk_bf16_f32 v66, v54, v55
	v_cvt_pk_bf16_f32 v67, v56, v57
	v_cvt_pk_bf16_f32 v68, v50, v51
	v_cvt_pk_bf16_f32 v69, v52, v53
	v_mov_b64_e32 v[50:51], v[174:175]
	v_mov_b64_e32 v[52:53], v[176:177]
	v_mov_b64_e32 v[54:55], v[178:179]
	v_mov_b64_e32 v[56:57], v[180:181]
	v_mul_f32_e32 v70, v103, v102
	v_mov_b32_e32 v92, v156
	v_mov_b32_e32 v93, v156
	s_waitcnt vmcnt(0)
	v_mul_f32_e32 v54, v54, v70
	v_mul_f32_e32 v70, v103, v101
	v_mul_f32_e32 v55, v55, v70
	v_mul_f32_e32 v70, v103, v100
	v_mul_f32_e32 v56, v56, v70
	v_mul_f32_e32 v70, v103, v99
	v_mul_f32_e32 v57, v57, v70
	v_mul_f32_e32 v70, v103, v98
	v_mul_f32_e32 v50, v50, v70
	v_mul_f32_e32 v70, v103, v97
	v_mul_f32_e32 v51, v51, v70
	v_mul_f32_e32 v70, v103, v96
	v_mul_f32_e32 v52, v52, v70
	v_mul_f32_e32 v70, v103, v95
	v_mul_f32_e32 v53, v53, v70
	v_cvt_pk_bf16_f32 v70, v54, v55
	v_cvt_pk_bf16_f32 v71, v56, v57
	v_cvt_pk_bf16_f32 v72, v50, v51
	v_cvt_pk_bf16_f32 v73, v52, v53
	v_mov_b64_e32 v[50:51], v[182:183]
	v_mov_b64_e32 v[52:53], v[184:185]
	v_mov_b64_e32 v[54:55], v[186:187]
	v_mov_b64_e32 v[56:57], v[188:189]
	v_mov_b32_e32 v95, v156
	v_mov_b32_e32 v96, v156
	v_mov_b32_e32 v97, v156
	s_waitcnt vmcnt(0)
	v_mul_f32_e32 v55, v55, v74
	v_mul_f32_e32 v74, v103, v77
	v_mul_f32_e32 v56, v56, v74
	v_mul_f32_e32 v74, v103, v76
	v_mul_f32_e32 v57, v57, v74
	v_mul_f32_e32 v74, v103, v83
	v_mul_f32_e32 v50, v50, v74
	v_mul_f32_e32 v74, v103, v82
	v_mul_f32_e32 v51, v74, v51
	v_mul_f32_e32 v74, v103, v85
	v_mul_f32_e32 v52, v74, v52
	v_mul_f32_e32 v74, v103, v84
	v_mul_f32_e32 v54, v54, v75
	v_mul_f32_e32 v53, v74, v53
	v_cvt_pk_bf16_f32 v74, v54, v55
	v_cvt_pk_bf16_f32 v75, v56, v57
	v_cvt_pk_bf16_f32 v76, v50, v51
	v_mad_i64_i32 v[50:51], s[0:1], v91, s20, v[78:79]
	v_lshl_add_u64 v[50:51], v[50:51], 0, s[34:35]
	v_lshl_add_u64 v[136:137], v[50:51], 0, v[62:63]
	v_mad_u64_u32 v[50:51], s[0:1], v90, s20, v[78:79]
	v_lshl_add_u64 v[50:51], v[50:51], 0, s[34:35]
	v_lshl_add_u64 v[50:51], v[50:51], 0, v[80:81]
	v_lshl_add_u64 v[138:139], v[50:51], 0, s[26:27]
	v_mad_i64_i32 v[50:51], s[0:1], v89, s20, v[78:79]
	v_lshl_add_u64 v[50:51], v[50:51], 0, s[34:35]
	v_lshl_add_u64 v[140:141], v[50:51], 0, v[62:63]
	v_mad_u64_u32 v[50:51], s[0:1], v88, s20, v[78:79]
	s_lshl_b32 s0, s4, 2
	v_readlane_b32 s1, v254, 12
	v_lshl_add_u64 v[50:51], v[50:51], 0, s[34:35]
	s_add_u32 s0, s1, s0
	v_readlane_b32 s1, v254, 13
	v_lshl_add_u64 v[50:51], v[50:51], 0, v[80:81]
	s_addc_u32 s1, s1, 0
	v_cvt_pk_bf16_f32 v77, v52, v53
	v_lshl_add_u64 v[142:143], v[50:51], 0, s[26:27]
	v_lshl_add_u64 v[144:145], s[0:1], 0, v[64:65]
	v_mov_b32_e32 v90, 0
	v_mov_b32_e32 v91, v156
	v_mov_b32_e32 v88, v156
	v_mov_b32_e32 v89, v156
	v_mov_b32_e32 v82, 0
	v_mov_b32_e32 v83, v156
	v_mov_b32_e32 v84, v156
	v_mov_b32_e32 v85, v156
	v_mov_b32_e32 v78, 0
	v_mov_b32_e32 v79, v156
	v_mov_b32_e32 v80, v156
	v_mov_b32_e32 v81, v156
	v_mov_b32_e32 v62, 0
	v_mov_b32_e32 v63, v156
	v_mov_b32_e32 v64, v156
	v_mov_b32_e32 v65, v156
	v_mov_b32_e32 v54, 0
	v_mov_b32_e32 v55, v156
	v_mov_b32_e32 v56, v156
	v_mov_b32_e32 v57, v156
	v_mov_b32_e32 v50, 0
	v_mov_b32_e32 v51, v156
	v_mov_b32_e32 v52, v156
	v_mov_b32_e32 v53, v156
	s_barrier
	s_branch .LBB0_449

.LBB0_547:
	v_and_b32_e32 v10, 15, v130
	v_ashrrev_i32_e32 v9, 8, v130
	v_and_or_b32 v12, v144, 48, v10
	v_add_u32_e32 v11, s54, v9
	v_or_b32_e32 v2, s16, v12
	v_lshl_add_u32 v148, v11, 6, v2
	v_mov_b64_e32 v[2:3], s[94:95]
	v_mad_i64_i32 v[2:3], s[2:3], v148, s20, v[2:3]
	s_lshl_b32 s34, s17, 1
	v_lshl_add_u64 v[4:5], v[2:3], 0, s[34:35]
	v_and_b32_e32 v2, 48, v6
	v_mov_b32_e32 v3, v0
	v_lshl_add_u64 v[2:3], v[4:5], 0, v[2:3]
	global_load_dwordx4 v[14:17], v[2:3], off
	global_load_dwordx4 v[18:21], v[2:3], off offset:64
	global_load_dwordx4 v[40:43], v[2:3], off offset:128
	global_load_dwordx4 v[76:79], v[2:3], off offset:192
	v_lshrrev_b32_e32 v13, 4, v6
	v_readlane_b32 s6, v252, 20
	v_lshlrev_b32_e32 v92, 5, v13
	v_readlane_b32 s7, v252, 21
	s_nop 4
	global_load_dwordx4 v[80:83], v92, s[6:7] offset:16
	global_load_dwordx4 v[84:87], v92, s[6:7]
	v_mov_b32_e32 v3, v0
	v_lshlrev_b32_e32 v2, 3, v13
	v_lshl_add_u64 v[4:5], v[4:5], 0, v[2:3]
	global_load_dwordx4 v[204:207], v92, s[6:7] offset:128
	global_load_dwordx4 v[208:211], v92, s[6:7] offset:144
	global_load_dwordx4 v[212:215], v92, s[6:7] offset:256
	global_load_dwordx4 v[216:219], v92, s[6:7] offset:272
	global_load_dwordx4 v[238:241], v92, s[6:7] offset:384
	global_load_dwordx4 v[242:245], v92, s[6:7] offset:400
	s_mov_b64 s[100:101], 0x1800
	v_lshl_add_u64 v[246:247], v[4:5], 0, s[100:101]
	global_load_dwordx2 v[150:151], v[246:247], off
	global_load_dwordx2 v[146:147], v[246:247], off offset:32
	global_load_dwordx2 v[142:143], v[246:247], off offset:64
	global_load_dwordx2 v[140:141], v[246:247], off offset:96
	global_load_dwordx2 v[138:139], v[246:247], off offset:128
	global_load_dwordx2 v[136:137], v[246:247], off offset:160
	global_load_dwordx2 v[134:135], v[246:247], off offset:192
	global_load_dwordx2 v[132:133], v[246:247], off offset:224
	v_cmp_lt_i32_e32 vcc, v234, v229
	s_mov_b64 s[2:3], 0x1800
	s_waitcnt vmcnt(0)
	v_and_b32_e32 v88, 0xffff0000, v14
	v_lshlrev_b32_e32 v3, 16, v14
	v_mul_f32_e32 v112, v88, v88
	v_lshlrev_b32_e32 v89, 16, v15
	v_fmac_f32_e32 v112, v3, v3
	v_and_b32_e32 v90, 0xffff0000, v15
	v_fmac_f32_e32 v112, v89, v89
	v_lshlrev_b32_e32 v91, 16, v16
	v_fmac_f32_e32 v112, v90, v90
	v_and_b32_e32 v93, 0xffff0000, v16
	v_fmac_f32_e32 v112, v91, v91
	v_lshlrev_b32_e32 v94, 16, v17
	v_fmac_f32_e32 v112, v93, v93
	v_and_b32_e32 v95, 0xffff0000, v17
	v_fmac_f32_e32 v112, v94, v94
	v_lshlrev_b32_e32 v96, 16, v18
	v_fmac_f32_e32 v112, v95, v95
	v_and_b32_e32 v97, 0xffff0000, v18
	v_fmac_f32_e32 v112, v96, v96
	v_lshlrev_b32_e32 v98, 16, v19
	v_fmac_f32_e32 v112, v97, v97
	v_and_b32_e32 v99, 0xffff0000, v19
	v_fmac_f32_e32 v112, v98, v98
	v_lshlrev_b32_e32 v100, 16, v20
	v_fmac_f32_e32 v112, v99, v99
	v_and_b32_e32 v101, 0xffff0000, v20
	v_fmac_f32_e32 v112, v100, v100
	v_lshlrev_b32_e32 v102, 16, v21
	v_fmac_f32_e32 v112, v101, v101
	v_and_b32_e32 v103, 0xffff0000, v21
	v_fmac_f32_e32 v112, v102, v102
	v_lshlrev_b32_e32 v104, 16, v40
	v_fmac_f32_e32 v112, v103, v103
	v_and_b32_e32 v105, 0xffff0000, v40
	v_fmac_f32_e32 v112, v104, v104
	v_lshlrev_b32_e32 v106, 16, v41
	v_fmac_f32_e32 v112, v105, v105
	v_and_b32_e32 v107, 0xffff0000, v41
	v_fmac_f32_e32 v112, v106, v106
	v_lshlrev_b32_e32 v108, 16, v42
	v_fmac_f32_e32 v112, v107, v107
	v_and_b32_e32 v109, 0xffff0000, v42
	v_fmac_f32_e32 v112, v108, v108
	v_lshlrev_b32_e32 v110, 16, v43
	v_fmac_f32_e32 v112, v109, v109
	v_and_b32_e32 v111, 0xffff0000, v43
	v_and_b32_e32 v40, 0xffff0000, v76
	v_lshlrev_b32_e32 v41, 16, v76
	v_fmac_f32_e32 v112, v110, v110
	v_pk_mul_f32 v[14:15], v[40:41], v[40:41]
	v_fmac_f32_e32 v112, v111, v111
	v_and_b32_e32 v42, 0xffff0000, v77
	v_lshlrev_b32_e32 v43, 16, v77
	v_add_f32_e32 v15, v15, v112
	v_pk_mul_f32 v[16:17], v[42:43], v[42:43]
	v_add_f32_e32 v14, v14, v15
	v_and_b32_e32 v76, 0xffff0000, v78
	v_lshlrev_b32_e32 v77, 16, v78
	v_add_f32_e32 v14, v17, v14
	v_pk_mul_f32 v[18:19], v[76:77], v[76:77]
	v_add_f32_e32 v14, v16, v14
	v_and_b32_e32 v78, 0xffff0000, v79
	v_lshlrev_b32_e32 v79, 16, v79
	v_add_f32_e32 v14, v19, v14
	v_pk_mul_f32 v[20:21], v[78:79], v[78:79]
	v_add_f32_e32 v14, v18, v14
	v_cndmask_b32_e32 v22, v228, v234, vcc
	v_add_f32_e32 v14, v21, v14
	v_lshlrev_b32_e32 v159, 2, v22
	v_add_f32_e32 v14, v20, v14
	ds_bpermute_b32 v15, v159, v14
	v_cmp_lt_i32_e32 vcc, v235, v229
	s_waitcnt lgkmcnt(0)
	v_add_f32_e32 v14, v14, v15
	v_cndmask_b32_e32 v23, v228, v235, vcc
	v_lshlrev_b32_e32 v158, 2, v23
	ds_bpermute_b32 v15, v158, v14
	v_lshl_add_u64 v[22:23], v[4:5], 0, s[2:3]
	s_movk_i32 s2, 0x1000
	v_add_co_u32_e32 v4, vcc, s2, v4
	s_waitcnt lgkmcnt(0)
	v_add_f32_e32 v14, v14, v15
	v_addc_co_u32_e32 v5, vcc, 0, v5, vcc
	v_fmamk_f32 v14, v14, 0x3c000000, v221
	s_mov_b32 s2, 0x800000
	v_mul_f32_e32 v15, 0x4b800000, v14
	v_cmp_gt_f32_e32 vcc, s2, v14
	v_cndmask_b32_e32 v14, v14, v15, vcc
	v_rsq_f32_e32 v14, v14
	s_movk_i32 s2, 0x1d1
	v_mul_f32_e32 v4, 0x45800000, v14
	v_cndmask_b32_e32 v4, v14, v4, vcc
	v_mul_f32_e32 v4, 0x3e0293ee, v4
	v_mul_f32_e32 v14, v4, v89
	v_mul_f32_e32 v15, v4, v90
	v_mul_f32_e32 v16, v4, v91
	v_mul_f32_e32 v17, v4, v93
	v_mul_f32_e32 v18, v4, v94
	v_mul_f32_e32 v19, v4, v95
	v_mul_f32_e32 v3, v4, v3
	v_mul_f32_e32 v5, v4, v88
	v_mul_f32_e32 v14, v86, v14
	v_mul_f32_e32 v15, v87, v15
	v_mul_f32_e32 v16, v80, v16
	v_mul_f32_e32 v17, v81, v17
	v_mul_f32_e32 v18, v82, v18
	v_mul_f32_e32 v19, v83, v19
	v_mul_f32_e32 v3, v84, v3
	v_mul_f32_e32 v5, v85, v5
	v_cvt_pk_bf16_f32 v80, v3, v5
	v_cvt_pk_bf16_f32 v81, v14, v15
	v_cvt_pk_bf16_f32 v82, v16, v17
	v_cvt_pk_bf16_f32 v83, v18, v19
	v_mov_b64_e32 v[14:15], v[204:205]
	v_mov_b64_e32 v[16:17], v[206:207]
	v_mov_b64_e32 v[18:19], v[208:209]
	v_mov_b64_e32 v[20:21], v[210:211]
	v_mul_f32_e32 v3, v4, v96
	v_mul_f32_e32 v5, v4, v97
	v_mul_f32_e32 v22, v4, v98
	v_mul_f32_e32 v23, v4, v99
	v_mul_f32_e32 v84, v4, v100
	v_mul_f32_e32 v85, v4, v101
	v_mul_f32_e32 v86, v4, v102
	v_mul_f32_e32 v87, v4, v103
	v_mul_f32_e32 v88, v4, v108
	v_mul_f32_e32 v89, v4, v109
	v_mul_f32_e32 v90, v4, v110
	v_mul_f32_e32 v91, v4, v111
	v_cmp_gt_i32_e32 vcc, s2, v130
	s_waitcnt vmcnt(1)
	v_mul_f32_e32 v3, v14, v3
	v_mul_f32_e32 v5, v15, v5
	v_mul_f32_e32 v14, v16, v22
	v_mul_f32_e32 v15, v17, v23
	s_waitcnt vmcnt(0)
	v_mul_f32_e32 v16, v18, v84
	v_mul_f32_e32 v17, v19, v85
	v_mul_f32_e32 v18, v20, v86
	v_mul_f32_e32 v19, v21, v87
	v_cvt_pk_bf16_f32 v84, v3, v5
	v_cvt_pk_bf16_f32 v85, v14, v15
	v_cvt_pk_bf16_f32 v86, v16, v17
	v_cvt_pk_bf16_f32 v87, v18, v19
	v_mov_b64_e32 v[14:15], v[212:213]
	v_mov_b64_e32 v[16:17], v[214:215]
	v_mov_b64_e32 v[18:19], v[216:217]
	v_mov_b64_e32 v[20:21], v[218:219]
	v_mul_f32_e32 v3, v4, v104
	v_mul_f32_e32 v5, v4, v105
	v_mul_f32_e32 v22, v4, v106
	v_mul_f32_e32 v23, v4, v107
	s_waitcnt vmcnt(1)
	v_mul_f32_e32 v3, v14, v3
	v_mul_f32_e32 v5, v15, v5
	v_mul_f32_e32 v14, v16, v22
	v_mul_f32_e32 v15, v17, v23
	s_waitcnt vmcnt(0)
	v_mul_f32_e32 v16, v18, v88
	v_mul_f32_e32 v17, v19, v89
	v_mul_f32_e32 v18, v20, v90
	v_mul_f32_e32 v19, v21, v91
	v_cvt_pk_bf16_f32 v88, v3, v5
	v_cvt_pk_bf16_f32 v89, v14, v15
	v_cvt_pk_bf16_f32 v90, v16, v17
	v_cvt_pk_bf16_f32 v91, v18, v19
	v_mov_b64_e32 v[14:15], v[238:239]
	v_mov_b64_e32 v[16:17], v[240:241]
	v_mov_b64_e32 v[18:19], v[242:243]
	v_mov_b64_e32 v[20:21], v[244:245]
	v_mul_f32_e32 v3, v4, v41
	v_mul_f32_e32 v5, v4, v40
	v_mul_f32_e32 v22, v4, v43
	v_mul_f32_e32 v23, v4, v42
	v_mul_f32_e32 v40, v4, v77
	v_mul_f32_e32 v41, v4, v76
	v_mul_f32_e32 v42, v4, v79
	v_mul_f32_e32 v4, v4, v78
	s_waitcnt vmcnt(1)
	v_mul_f32_e32 v3, v14, v3
	v_mul_f32_e32 v5, v15, v5
	v_mul_f32_e32 v14, v16, v22
	v_mul_f32_e32 v15, v17, v23
	s_waitcnt vmcnt(0)
	v_mul_f32_e32 v16, v18, v40
	v_mul_f32_e32 v17, v41, v19
	v_mul_f32_e32 v18, v42, v20
	v_mul_f32_e32 v4, v4, v21
	v_cvt_pk_bf16_f32 v92, v3, v5
	v_cvt_pk_bf16_f32 v93, v14, v15
	v_cvt_pk_bf16_f32 v94, v16, v17
	v_cvt_pk_bf16_f32 v95, v18, v4
	s_barrier
	s_and_saveexec_b64 s[2:3], vcc
	s_cbranch_execz .LBB0_555
	v_max_i32_e32 v3, 0xffffffd1, v130
	v_sub_u32_e32 v3, v3, v130
	v_add_u32_e32 v3, 0x1ff, v3
	v_cmp_lt_u32_e32 vcc, s46, v3
	s_mov_b64 s[22:23], -1
	v_mov_b32_e32 v4, v130
	s_and_saveexec_b64 s[16:17], vcc
	s_cbranch_execz .LBB0_552
	v_readlane_b32 s5, v252, 19
	s_or_b32 s5, s28, s5
	s_mul_i32 s22, s5, 0x1d1
	s_mov_b32 s23, s35
	v_lshrrev_b32_e32 v3, 9, v3
	s_lshl_b64 s[22:23], s[22:23], 2
	v_add_u32_e32 v3, 1, v3
	s_add_u32 s22, s72, s22
	v_and_b32_e32 v14, 0xfffffe, v3
	v_add_u32_e32 v131, 0x200, v130
	v_readlane_b32 s5, v254, 63
	s_addc_u32 s23, s73, s23
	s_mov_b64 s[24:25], 0
	v_lshl_add_u32 v15, v130, 2, s5
	v_mov_b32_e32 v16, v14
	v_mov_b64_e32 v[4:5], v[130:131]
